# each workgroup writes back L2 at its own grid-barrier arrival (early wbl2)
# baseline (speedup 1.0000x reference)
; __device__ __forceinline__ unsigned xb_add(unsigned* p, unsigned v) { return __hip_atomic_fetch_add(p, v, __ATOMIC_RELAXED, __HIP_MEMORY_SCOPE_AGENT); }
; __device__ __forceinline__ void xcd_barrier(const XcdBarrier& b) {
;     ...
;     if (threadIdx.x == 0) {
;         unsigned* bar = b.bar;
;         __builtin_amdgcn_s_waitcnt(0);
;         unsigned nloc = b.st[0], nx = b.st[1];
;         if (nloc == 0u) { xcd_barrier_complete(bar, b.x, nloc, nx); b.st[0] = nloc; b.st[1] = nx; }
;         const unsigned old = xb_add(&bar[XB_XSUB(b.x)], 1u);
;         const unsigned gen = old / nloc;
.LBB0_270:
	s_mov_b64 s[4:5], exec
	s_lshl_b32 s6, s33, 8
	v_readlane_b32 s8, v252, 10
	v_mbcnt_lo_u32_b32 v1, s4, 0
	v_readlane_b32 s9, v252, 11
	s_add_u32 s22, s8, s6
	v_mbcnt_hi_u32_b32 v1, s5, v1
	s_addc_u32 s23, s9, 0
	v_cmp_eq_u32_e32 vcc, 0, v1
	s_and_saveexec_b64 s[6:7], vcc
	s_cbranch_execz .LBB0_272
	s_bcnt1_i32_b64 s4, s[4:5]
	v_mov_b32_e32 v3, 0x1000
	v_mov_b32_e32 v4, s4
	buffer_wbl2 sc1
	s_waitcnt vmcnt(0)
	global_atomic_add v3, v3, v4, s[22:23] offset:1024 sc0

; __device__ __forceinline__ unsigned xb_add(unsigned* p, unsigned v) { return __hip_atomic_fetch_add(p, v, __ATOMIC_RELAXED, __HIP_MEMORY_SCOPE_AGENT); }
; __device__ __forceinline__ void xcd_barrier(const XcdBarrier& b) {
;     ...
;     if (threadIdx.x == 0) {
;         unsigned* bar = b.bar;
;         __builtin_amdgcn_s_waitcnt(0);
;         unsigned nloc = b.st[0], nx = b.st[1];
;         if (nloc == 0u) { xcd_barrier_complete(bar, b.x, nloc, nx); b.st[0] = nloc; b.st[1] = nx; }
;         const unsigned old = xb_add(&bar[XB_XSUB(b.x)], 1u);
;         const unsigned gen = old / nloc;
.LBB0_721:
	s_mov_b64 s[2:3], exec
	s_lshl_b32 s4, s8, 8
	v_readlane_b32 s6, v252, 10
	v_mbcnt_lo_u32_b32 v0, s2, 0
	v_readlane_b32 s7, v252, 11
	s_add_u32 s4, s6, s4
	v_mbcnt_hi_u32_b32 v0, s3, v0
	s_addc_u32 s5, s7, 0
	v_cmp_eq_u32_e32 vcc, 0, v0
	s_and_saveexec_b64 s[6:7], vcc
	s_cbranch_execz .LBB0_723
	s_bcnt1_i32_b64 s2, s[2:3]
	v_mov_b32_e32 v4, s2
	v_mov_b32_e32 v5, 0x1000
	buffer_wbl2 sc1
	s_waitcnt vmcnt(0)
	global_atomic_add v4, v5, v4, s[4:5] offset:1024 sc0
